# misc routine pipeline deepened: three LDS buffers, W and HX of two chunks ahead in flight (prefetch distance 2)
# baseline (speedup 1.0000x reference)
.Lmisc_any:
	s_cmpk_gt_u32 s48, 0x87
	s_cbranch_scc1 .Lmisc_done
	v_readfirstlane_b32 s4, v190
	s_lshr_b32 s4, s4, 6
	s_load_dwordx2 s[2:3], s[0:1], 0x100
	v_and_b32_e32 v0, 0x1ff, v190
	v_and_b32_e32 v10, 63, v0
	v_and_b32_e32 v11, 15, v10
	v_lshrrev_b32_e32 v3, 4, v10
	v_lshlrev_b32_e32 v3, 4, v3
	v_mul_u32_u24_e32 v2, 0x140, v11
	v_add_u32_e32 v2, v2, v3
	v_lshl_add_u32 v1, v11, 12, v3
	v_mul_u32_u24_e32 v8, 0x210, v11
	v_add_u32_e32 v8, v8, v3
	v_add_u32_e32 v9, 0xa500, v8
	v_add_u32_e32 v15, 0x14a00, v8
	v_lshrrev_b32_e32 v12, 5, v0
	v_and_b32_e32 v13, 31, v0
	v_lshlrev_b32_e32 v13, 4, v13
	v_lshl_add_u32 v5, v12, 12, v13
	v_mul_u32_u24_e32 v6, 0x210, v12
	v_add_u32_e32 v6, v6, v13
	v_add_u32_e32 v7, 0xa500, v6
	v_add_u32_e32 v14, 0x14a00, v6
	s_waitcnt lgkmcnt(0)
	s_add_u32 s18, s2, 0x1000000
	s_addc_u32 s19, s3, 0
	s_add_u32 s28, s2, 0x1010000
	s_addc_u32 s29, s3, 0
	s_add_u32 s30, s2, 0x1020000
	s_addc_u32 s31, s3, 0
	s_add_u32 s34, s2, 0x1030000
	s_addc_u32 s35, s3, 0
	s_add_u32 s36, s2, 0x1040000
	s_addc_u32 s37, s3, 0
	s_add_u32 s38, s2, 0x8884000
	s_addc_u32 s39, s3, 0
.Lmisc_pass:
	s_lshl_b32 s5, s48, 3
	s_add_i32 s5, s5, s4
	s_lshl_b32 s6, s5, 16
	s_lshr_b32 s7, s5, 16
	s_add_u32 s8, s2, s6
	s_addc_u32 s9, s3, s7
	s_add_u32 s8, s8, 0xe144d00
	s_addc_u32 s9, s9, 0
	s_mul_i32 s6, s5, 0x1400
	s_add_u32 s40, s2, s6
	s_addc_u32 s41, s3, 0
	s_add_u32 s40, s40, 0x21344d00
	s_addc_u32 s41, s41, 0
	v_mov_b64_e32 v[32:33], 0
	v_mov_b64_e32 v[34:35], 0
	v_mov_b64_e32 v[36:37], 0
	v_mov_b64_e32 v[38:39], 0
	v_mov_b64_e32 v[40:41], 0
	v_mov_b64_e32 v[42:43], 0
	v_mov_b64_e32 v[44:45], 0
	v_mov_b64_e32 v[46:47], 0
	v_mov_b64_e32 v[48:49], 0
	v_mov_b64_e32 v[50:51], 0
	global_load_dwordx4 v[148:151], v5, s[18:19]
	global_load_dwordx4 v[152:155], v5, s[28:29]
	global_load_dwordx4 v[156:159], v5, s[30:31]
	global_load_dwordx4 v[22:25], v5, s[34:35]
	global_load_dwordx4 v[26:29], v5, s[36:37]
	global_load_dwordx4 v[52:55], v1, s[8:9]
	global_load_dwordx4 v[56:59], v1, s[8:9] offset:64
	global_load_dwordx4 v[60:63], v1, s[8:9] offset:128
	global_load_dwordx4 v[64:67], v1, s[8:9] offset:192
	global_load_dwordx4 v[68:71], v1, s[8:9] offset:256
	global_load_dwordx4 v[72:75], v1, s[8:9] offset:320
	global_load_dwordx4 v[76:79], v1, s[8:9] offset:384
	global_load_dwordx4 v[80:83], v1, s[8:9] offset:448
	global_load_dwordx4 v[172:175], v5, s[18:19] offset:512
	global_load_dwordx4 v[176:179], v5, s[28:29] offset:512
	global_load_dwordx4 v[180:183], v5, s[30:31] offset:512
	global_load_dwordx4 v[184:187], v5, s[34:35] offset:512
	global_load_dwordx4 v[196:199], v5, s[36:37] offset:512
	global_load_dwordx4 v[84:87], v1, s[8:9] offset:512
	global_load_dwordx4 v[88:91], v1, s[8:9] offset:576
	global_load_dwordx4 v[92:95], v1, s[8:9] offset:640
	global_load_dwordx4 v[96:99], v1, s[8:9] offset:704
	global_load_dwordx4 v[100:103], v1, s[8:9] offset:768
	global_load_dwordx4 v[104:107], v1, s[8:9] offset:832
	global_load_dwordx4 v[108:111], v1, s[8:9] offset:896
	global_load_dwordx4 v[112:115], v1, s[8:9] offset:960
	s_waitcnt vmcnt(21)
	ds_write_b128 v6, v[148:151]
	ds_write_b128 v6, v[152:155] offset:8448
	ds_write_b128 v6, v[156:159] offset:16896
	ds_write_b128 v6, v[22:25] offset:25344
	ds_write_b128 v6, v[26:29] offset:33792
	s_waitcnt lgkmcnt(0)
	s_barrier
	global_load_dwordx4 v[148:151], v5, s[18:19] offset:1024
	global_load_dwordx4 v[152:155], v5, s[28:29] offset:1024
	global_load_dwordx4 v[156:159], v5, s[30:31] offset:1024
	global_load_dwordx4 v[22:25], v5, s[34:35] offset:1024
	global_load_dwordx4 v[26:29], v5, s[36:37] offset:1024
	global_load_dwordx4 v[116:119], v1, s[8:9] offset:1024
	global_load_dwordx4 v[120:123], v1, s[8:9] offset:1088
	global_load_dwordx4 v[124:127], v1, s[8:9] offset:1152
	global_load_dwordx4 v[128:131], v1, s[8:9] offset:1216
	global_load_dwordx4 v[132:135], v1, s[8:9] offset:1280
	global_load_dwordx4 v[136:139], v1, s[8:9] offset:1344
	global_load_dwordx4 v[140:143], v1, s[8:9] offset:1408
	global_load_dwordx4 v[144:147], v1, s[8:9] offset:1472
	s_waitcnt vmcnt(26)
	ds_read_b128 v[200:203], v8
	ds_read_b128 v[204:207], v8 offset:8448
	ds_read_b128 v[208:211], v8 offset:16896
	ds_read_b128 v[212:215], v8 offset:25344
	ds_read_b128 v[234:237], v8 offset:33792
	ds_read_b128 v[238:241], v8 offset:64
	ds_read_b128 v[242:245], v8 offset:8512
	ds_read_b128 v[246:249], v8 offset:16960
	s_waitcnt lgkmcnt(7)
	v_mfma_f32_16x16x32_bf16 v[32:35], v[200:203], v[52:55], v[32:35]
	ds_read_b128 v[200:203], v8 offset:25408
	s_waitcnt lgkmcnt(7)
	v_mfma_f32_16x16x32_bf16 v[36:39], v[204:207], v[52:55], v[36:39]
	ds_read_b128 v[204:207], v8 offset:33856
	s_waitcnt lgkmcnt(7)
	v_mfma_f32_16x16x32_bf16 v[40:43], v[208:211], v[52:55], v[40:43]
	ds_read_b128 v[208:211], v8 offset:128
	s_waitcnt lgkmcnt(7)
	v_mfma_f32_16x16x32_bf16 v[44:47], v[212:215], v[52:55], v[44:47]
	ds_read_b128 v[212:215], v8 offset:8576
	s_waitcnt lgkmcnt(7)
	v_mfma_f32_16x16x32_bf16 v[48:51], v[234:237], v[52:55], v[48:51]
	ds_read_b128 v[234:237], v8 offset:17024
	s_waitcnt lgkmcnt(7)
	v_mfma_f32_16x16x32_bf16 v[32:35], v[238:241], v[56:59], v[32:35]
	ds_read_b128 v[238:241], v8 offset:25472
	s_waitcnt lgkmcnt(7)
	v_mfma_f32_16x16x32_bf16 v[36:39], v[242:245], v[56:59], v[36:39]
	ds_read_b128 v[242:245], v8 offset:33920
	s_waitcnt lgkmcnt(7)
	v_mfma_f32_16x16x32_bf16 v[40:43], v[246:249], v[56:59], v[40:43]
	ds_read_b128 v[246:249], v8 offset:192
	s_waitcnt lgkmcnt(7)
	v_mfma_f32_16x16x32_bf16 v[44:47], v[200:203], v[56:59], v[44:47]
	ds_read_b128 v[200:203], v8 offset:8640
	s_waitcnt lgkmcnt(7)
	v_mfma_f32_16x16x32_bf16 v[48:51], v[204:207], v[56:59], v[48:51]
	ds_read_b128 v[204:207], v8 offset:17088
	s_waitcnt lgkmcnt(7)
	v_mfma_f32_16x16x32_bf16 v[32:35], v[208:211], v[60:63], v[32:35]
	ds_read_b128 v[208:211], v8 offset:25536
	s_waitcnt lgkmcnt(7)
	v_mfma_f32_16x16x32_bf16 v[36:39], v[212:215], v[60:63], v[36:39]
	ds_read_b128 v[212:215], v8 offset:33984
	s_waitcnt lgkmcnt(7)
	v_mfma_f32_16x16x32_bf16 v[40:43], v[234:237], v[60:63], v[40:43]
	ds_read_b128 v[234:237], v8 offset:256
	s_waitcnt lgkmcnt(7)
	v_mfma_f32_16x16x32_bf16 v[44:47], v[238:241], v[60:63], v[44:47]
	ds_read_b128 v[238:241], v8 offset:8704
	s_waitcnt lgkmcnt(7)
	v_mfma_f32_16x16x32_bf16 v[48:51], v[242:245], v[60:63], v[48:51]
	ds_read_b128 v[242:245], v8 offset:17152
	s_waitcnt lgkmcnt(7)
	v_mfma_f32_16x16x32_bf16 v[32:35], v[246:249], v[64:67], v[32:35]
	ds_read_b128 v[246:249], v8 offset:25600
	s_waitcnt lgkmcnt(7)
	v_mfma_f32_16x16x32_bf16 v[36:39], v[200:203], v[64:67], v[36:39]
	ds_read_b128 v[200:203], v8 offset:34048
	s_waitcnt lgkmcnt(7)
	v_mfma_f32_16x16x32_bf16 v[40:43], v[204:207], v[64:67], v[40:43]
	ds_read_b128 v[204:207], v8 offset:320
	s_waitcnt lgkmcnt(7)
	v_mfma_f32_16x16x32_bf16 v[44:47], v[208:211], v[64:67], v[44:47]
	ds_read_b128 v[208:211], v8 offset:8768
	s_waitcnt lgkmcnt(7)
	v_mfma_f32_16x16x32_bf16 v[48:51], v[212:215], v[64:67], v[48:51]
	ds_read_b128 v[212:215], v8 offset:17216
	s_waitcnt lgkmcnt(7)
	v_mfma_f32_16x16x32_bf16 v[32:35], v[234:237], v[68:71], v[32:35]
	ds_read_b128 v[234:237], v8 offset:25664
	s_waitcnt lgkmcnt(7)
	v_mfma_f32_16x16x32_bf16 v[36:39], v[238:241], v[68:71], v[36:39]
	ds_read_b128 v[238:241], v8 offset:34112
	s_waitcnt lgkmcnt(7)
	v_mfma_f32_16x16x32_bf16 v[40:43], v[242:245], v[68:71], v[40:43]
	ds_read_b128 v[242:245], v8 offset:384
	s_waitcnt lgkmcnt(7)
	v_mfma_f32_16x16x32_bf16 v[44:47], v[246:249], v[68:71], v[44:47]
	ds_read_b128 v[246:249], v8 offset:8832
	s_waitcnt lgkmcnt(7)
	v_mfma_f32_16x16x32_bf16 v[48:51], v[200:203], v[68:71], v[48:51]
	ds_read_b128 v[200:203], v8 offset:17280
	s_waitcnt lgkmcnt(7)
	v_mfma_f32_16x16x32_bf16 v[32:35], v[204:207], v[72:75], v[32:35]
	ds_read_b128 v[204:207], v8 offset:25728
	s_waitcnt lgkmcnt(7)
	v_mfma_f32_16x16x32_bf16 v[36:39], v[208:211], v[72:75], v[36:39]
	ds_read_b128 v[208:211], v8 offset:34176
	s_waitcnt lgkmcnt(7)
	v_mfma_f32_16x16x32_bf16 v[40:43], v[212:215], v[72:75], v[40:43]
	ds_read_b128 v[212:215], v8 offset:448
	s_waitcnt lgkmcnt(7)
	v_mfma_f32_16x16x32_bf16 v[44:47], v[234:237], v[72:75], v[44:47]
	ds_read_b128 v[234:237], v8 offset:8896
	s_waitcnt lgkmcnt(7)
	v_mfma_f32_16x16x32_bf16 v[48:51], v[238:241], v[72:75], v[48:51]
	ds_read_b128 v[238:241], v8 offset:17344
	s_waitcnt lgkmcnt(7)
	v_mfma_f32_16x16x32_bf16 v[32:35], v[242:245], v[76:79], v[32:35]
	ds_read_b128 v[242:245], v8 offset:25792
	s_waitcnt lgkmcnt(7)
	v_mfma_f32_16x16x32_bf16 v[36:39], v[246:249], v[76:79], v[36:39]
	ds_read_b128 v[246:249], v8 offset:34240
	s_waitcnt lgkmcnt(7)
	v_mfma_f32_16x16x32_bf16 v[40:43], v[200:203], v[76:79], v[40:43]
	s_waitcnt lgkmcnt(6)
	v_mfma_f32_16x16x32_bf16 v[44:47], v[204:207], v[76:79], v[44:47]
	s_waitcnt lgkmcnt(5)
	v_mfma_f32_16x16x32_bf16 v[48:51], v[208:211], v[76:79], v[48:51]
	s_waitcnt lgkmcnt(4)
	v_mfma_f32_16x16x32_bf16 v[32:35], v[212:215], v[80:83], v[32:35]
	s_waitcnt lgkmcnt(3)
	v_mfma_f32_16x16x32_bf16 v[36:39], v[234:237], v[80:83], v[36:39]
	s_waitcnt lgkmcnt(2)
	v_mfma_f32_16x16x32_bf16 v[40:43], v[238:241], v[80:83], v[40:43]
	s_waitcnt lgkmcnt(1)
	v_mfma_f32_16x16x32_bf16 v[44:47], v[242:245], v[80:83], v[44:47]
	s_waitcnt lgkmcnt(0)
	v_mfma_f32_16x16x32_bf16 v[48:51], v[246:249], v[80:83], v[48:51]
	s_waitcnt vmcnt(21)
	ds_write_b128 v7, v[172:175]
	ds_write_b128 v7, v[176:179] offset:8448
	ds_write_b128 v7, v[180:183] offset:16896
	ds_write_b128 v7, v[184:187] offset:25344
	ds_write_b128 v7, v[196:199] offset:33792
	s_waitcnt lgkmcnt(0)
	s_barrier
	global_load_dwordx4 v[172:175], v5, s[18:19] offset:1536
	global_load_dwordx4 v[176:179], v5, s[28:29] offset:1536
	global_load_dwordx4 v[180:183], v5, s[30:31] offset:1536
	global_load_dwordx4 v[184:187], v5, s[34:35] offset:1536
	global_load_dwordx4 v[196:199], v5, s[36:37] offset:1536
	global_load_dwordx4 v[52:55], v1, s[8:9] offset:1536
	global_load_dwordx4 v[56:59], v1, s[8:9] offset:1600
	global_load_dwordx4 v[60:63], v1, s[8:9] offset:1664
	global_load_dwordx4 v[64:67], v1, s[8:9] offset:1728
	global_load_dwordx4 v[68:71], v1, s[8:9] offset:1792
	global_load_dwordx4 v[72:75], v1, s[8:9] offset:1856
	global_load_dwordx4 v[76:79], v1, s[8:9] offset:1920
	global_load_dwordx4 v[80:83], v1, s[8:9] offset:1984
	s_waitcnt vmcnt(26)
	ds_read_b128 v[200:203], v9
	ds_read_b128 v[204:207], v9 offset:8448
	ds_read_b128 v[208:211], v9 offset:16896
	ds_read_b128 v[212:215], v9 offset:25344
	ds_read_b128 v[234:237], v9 offset:33792
	ds_read_b128 v[238:241], v9 offset:64
	ds_read_b128 v[242:245], v9 offset:8512
	ds_read_b128 v[246:249], v9 offset:16960
	s_waitcnt lgkmcnt(7)
	v_mfma_f32_16x16x32_bf16 v[32:35], v[200:203], v[84:87], v[32:35]
	ds_read_b128 v[200:203], v9 offset:25408
	s_waitcnt lgkmcnt(7)
	v_mfma_f32_16x16x32_bf16 v[36:39], v[204:207], v[84:87], v[36:39]
	ds_read_b128 v[204:207], v9 offset:33856
	s_waitcnt lgkmcnt(7)
	v_mfma_f32_16x16x32_bf16 v[40:43], v[208:211], v[84:87], v[40:43]
	ds_read_b128 v[208:211], v9 offset:128
	s_waitcnt lgkmcnt(7)
	v_mfma_f32_16x16x32_bf16 v[44:47], v[212:215], v[84:87], v[44:47]
	ds_read_b128 v[212:215], v9 offset:8576
	s_waitcnt lgkmcnt(7)
	v_mfma_f32_16x16x32_bf16 v[48:51], v[234:237], v[84:87], v[48:51]
	ds_read_b128 v[234:237], v9 offset:17024
	s_waitcnt lgkmcnt(7)
	v_mfma_f32_16x16x32_bf16 v[32:35], v[238:241], v[88:91], v[32:35]
	ds_read_b128 v[238:241], v9 offset:25472
	s_waitcnt lgkmcnt(7)
	v_mfma_f32_16x16x32_bf16 v[36:39], v[242:245], v[88:91], v[36:39]
	ds_read_b128 v[242:245], v9 offset:33920
	s_waitcnt lgkmcnt(7)
	v_mfma_f32_16x16x32_bf16 v[40:43], v[246:249], v[88:91], v[40:43]
	ds_read_b128 v[246:249], v9 offset:192
	s_waitcnt lgkmcnt(7)
	v_mfma_f32_16x16x32_bf16 v[44:47], v[200:203], v[88:91], v[44:47]
	ds_read_b128 v[200:203], v9 offset:8640
	s_waitcnt lgkmcnt(7)
	v_mfma_f32_16x16x32_bf16 v[48:51], v[204:207], v[88:91], v[48:51]
	ds_read_b128 v[204:207], v9 offset:17088
	s_waitcnt lgkmcnt(7)
	v_mfma_f32_16x16x32_bf16 v[32:35], v[208:211], v[92:95], v[32:35]
	ds_read_b128 v[208:211], v9 offset:25536
	s_waitcnt lgkmcnt(7)
	v_mfma_f32_16x16x32_bf16 v[36:39], v[212:215], v[92:95], v[36:39]
	ds_read_b128 v[212:215], v9 offset:33984
	s_waitcnt lgkmcnt(7)
	v_mfma_f32_16x16x32_bf16 v[40:43], v[234:237], v[92:95], v[40:43]
	ds_read_b128 v[234:237], v9 offset:256
	s_waitcnt lgkmcnt(7)
	v_mfma_f32_16x16x32_bf16 v[44:47], v[238:241], v[92:95], v[44:47]
	ds_read_b128 v[238:241], v9 offset:8704
	s_waitcnt lgkmcnt(7)
	v_mfma_f32_16x16x32_bf16 v[48:51], v[242:245], v[92:95], v[48:51]
	ds_read_b128 v[242:245], v9 offset:17152
	s_waitcnt lgkmcnt(7)
	v_mfma_f32_16x16x32_bf16 v[32:35], v[246:249], v[96:99], v[32:35]
	ds_read_b128 v[246:249], v9 offset:25600
	s_waitcnt lgkmcnt(7)
	v_mfma_f32_16x16x32_bf16 v[36:39], v[200:203], v[96:99], v[36:39]
	ds_read_b128 v[200:203], v9 offset:34048
	s_waitcnt lgkmcnt(7)
	v_mfma_f32_16x16x32_bf16 v[40:43], v[204:207], v[96:99], v[40:43]
	ds_read_b128 v[204:207], v9 offset:320
	s_waitcnt lgkmcnt(7)
	v_mfma_f32_16x16x32_bf16 v[44:47], v[208:211], v[96:99], v[44:47]
	ds_read_b128 v[208:211], v9 offset:8768
	s_waitcnt lgkmcnt(7)
	v_mfma_f32_16x16x32_bf16 v[48:51], v[212:215], v[96:99], v[48:51]
	ds_read_b128 v[212:215], v9 offset:17216
	s_waitcnt lgkmcnt(7)
	v_mfma_f32_16x16x32_bf16 v[32:35], v[234:237], v[100:103], v[32:35]
	ds_read_b128 v[234:237], v9 offset:25664
	s_waitcnt lgkmcnt(7)
	v_mfma_f32_16x16x32_bf16 v[36:39], v[238:241], v[100:103], v[36:39]
	ds_read_b128 v[238:241], v9 offset:34112
	s_waitcnt lgkmcnt(7)
	v_mfma_f32_16x16x32_bf16 v[40:43], v[242:245], v[100:103], v[40:43]
	ds_read_b128 v[242:245], v9 offset:384
	s_waitcnt lgkmcnt(7)
	v_mfma_f32_16x16x32_bf16 v[44:47], v[246:249], v[100:103], v[44:47]
	ds_read_b128 v[246:249], v9 offset:8832
	s_waitcnt lgkmcnt(7)
	v_mfma_f32_16x16x32_bf16 v[48:51], v[200:203], v[100:103], v[48:51]
	ds_read_b128 v[200:203], v9 offset:17280
	s_waitcnt lgkmcnt(7)
	v_mfma_f32_16x16x32_bf16 v[32:35], v[204:207], v[104:107], v[32:35]
	ds_read_b128 v[204:207], v9 offset:25728
	s_waitcnt lgkmcnt(7)
	v_mfma_f32_16x16x32_bf16 v[36:39], v[208:211], v[104:107], v[36:39]
	ds_read_b128 v[208:211], v9 offset:34176
	s_waitcnt lgkmcnt(7)
	v_mfma_f32_16x16x32_bf16 v[40:43], v[212:215], v[104:107], v[40:43]
	ds_read_b128 v[212:215], v9 offset:448
	s_waitcnt lgkmcnt(7)
	v_mfma_f32_16x16x32_bf16 v[44:47], v[234:237], v[104:107], v[44:47]
	ds_read_b128 v[234:237], v9 offset:8896
	s_waitcnt lgkmcnt(7)
	v_mfma_f32_16x16x32_bf16 v[48:51], v[238:241], v[104:107], v[48:51]
	ds_read_b128 v[238:241], v9 offset:17344
	s_waitcnt lgkmcnt(7)
	v_mfma_f32_16x16x32_bf16 v[32:35], v[242:245], v[108:111], v[32:35]
	ds_read_b128 v[242:245], v9 offset:25792
	s_waitcnt lgkmcnt(7)
	v_mfma_f32_16x16x32_bf16 v[36:39], v[246:249], v[108:111], v[36:39]
	ds_read_b128 v[246:249], v9 offset:34240
	s_waitcnt lgkmcnt(7)
	v_mfma_f32_16x16x32_bf16 v[40:43], v[200:203], v[108:111], v[40:43]
	s_waitcnt lgkmcnt(6)
	v_mfma_f32_16x16x32_bf16 v[44:47], v[204:207], v[108:111], v[44:47]
	s_waitcnt lgkmcnt(5)
	v_mfma_f32_16x16x32_bf16 v[48:51], v[208:211], v[108:111], v[48:51]
	s_waitcnt lgkmcnt(4)
	v_mfma_f32_16x16x32_bf16 v[32:35], v[212:215], v[112:115], v[32:35]
	s_waitcnt lgkmcnt(3)
	v_mfma_f32_16x16x32_bf16 v[36:39], v[234:237], v[112:115], v[36:39]
	s_waitcnt lgkmcnt(2)
	v_mfma_f32_16x16x32_bf16 v[40:43], v[238:241], v[112:115], v[40:43]
	s_waitcnt lgkmcnt(1)
	v_mfma_f32_16x16x32_bf16 v[44:47], v[242:245], v[112:115], v[44:47]
	s_waitcnt lgkmcnt(0)
	v_mfma_f32_16x16x32_bf16 v[48:51], v[246:249], v[112:115], v[48:51]
	s_waitcnt vmcnt(21)
	ds_write_b128 v14, v[148:151]
	ds_write_b128 v14, v[152:155] offset:8448
	ds_write_b128 v14, v[156:159] offset:16896
	ds_write_b128 v14, v[22:25] offset:25344
	ds_write_b128 v14, v[26:29] offset:33792
	s_waitcnt lgkmcnt(0)
	s_barrier
	global_load_dwordx4 v[148:151], v5, s[18:19] offset:2048
	global_load_dwordx4 v[152:155], v5, s[28:29] offset:2048
	global_load_dwordx4 v[156:159], v5, s[30:31] offset:2048
	global_load_dwordx4 v[22:25], v5, s[34:35] offset:2048
	global_load_dwordx4 v[26:29], v5, s[36:37] offset:2048
	global_load_dwordx4 v[84:87], v1, s[8:9] offset:2048
	global_load_dwordx4 v[88:91], v1, s[8:9] offset:2112
	global_load_dwordx4 v[92:95], v1, s[8:9] offset:2176
	global_load_dwordx4 v[96:99], v1, s[8:9] offset:2240
	global_load_dwordx4 v[100:103], v1, s[8:9] offset:2304
	global_load_dwordx4 v[104:107], v1, s[8:9] offset:2368
	global_load_dwordx4 v[108:111], v1, s[8:9] offset:2432
	global_load_dwordx4 v[112:115], v1, s[8:9] offset:2496
	s_waitcnt vmcnt(26)
	ds_read_b128 v[200:203], v15
	ds_read_b128 v[204:207], v15 offset:8448
	ds_read_b128 v[208:211], v15 offset:16896
	ds_read_b128 v[212:215], v15 offset:25344
	ds_read_b128 v[234:237], v15 offset:33792
	ds_read_b128 v[238:241], v15 offset:64
	ds_read_b128 v[242:245], v15 offset:8512
	ds_read_b128 v[246:249], v15 offset:16960
	s_waitcnt lgkmcnt(7)
	v_mfma_f32_16x16x32_bf16 v[32:35], v[200:203], v[116:119], v[32:35]
	ds_read_b128 v[200:203], v15 offset:25408
	s_waitcnt lgkmcnt(7)
	v_mfma_f32_16x16x32_bf16 v[36:39], v[204:207], v[116:119], v[36:39]
	ds_read_b128 v[204:207], v15 offset:33856
	s_waitcnt lgkmcnt(7)
	v_mfma_f32_16x16x32_bf16 v[40:43], v[208:211], v[116:119], v[40:43]
	ds_read_b128 v[208:211], v15 offset:128
	s_waitcnt lgkmcnt(7)
	v_mfma_f32_16x16x32_bf16 v[44:47], v[212:215], v[116:119], v[44:47]
	ds_read_b128 v[212:215], v15 offset:8576
	s_waitcnt lgkmcnt(7)
	v_mfma_f32_16x16x32_bf16 v[48:51], v[234:237], v[116:119], v[48:51]
	ds_read_b128 v[234:237], v15 offset:17024
	s_waitcnt lgkmcnt(7)
	v_mfma_f32_16x16x32_bf16 v[32:35], v[238:241], v[120:123], v[32:35]
	ds_read_b128 v[238:241], v15 offset:25472
	s_waitcnt lgkmcnt(7)
	v_mfma_f32_16x16x32_bf16 v[36:39], v[242:245], v[120:123], v[36:39]
	ds_read_b128 v[242:245], v15 offset:33920
	s_waitcnt lgkmcnt(7)
	v_mfma_f32_16x16x32_bf16 v[40:43], v[246:249], v[120:123], v[40:43]
	ds_read_b128 v[246:249], v15 offset:192
	s_waitcnt lgkmcnt(7)
	v_mfma_f32_16x16x32_bf16 v[44:47], v[200:203], v[120:123], v[44:47]
	ds_read_b128 v[200:203], v15 offset:8640
	s_waitcnt lgkmcnt(7)
	v_mfma_f32_16x16x32_bf16 v[48:51], v[204:207], v[120:123], v[48:51]
	ds_read_b128 v[204:207], v15 offset:17088
	s_waitcnt lgkmcnt(7)
	v_mfma_f32_16x16x32_bf16 v[32:35], v[208:211], v[124:127], v[32:35]
	ds_read_b128 v[208:211], v15 offset:25536
	s_waitcnt lgkmcnt(7)
	v_mfma_f32_16x16x32_bf16 v[36:39], v[212:215], v[124:127], v[36:39]
	ds_read_b128 v[212:215], v15 offset:33984
	s_waitcnt lgkmcnt(7)
	v_mfma_f32_16x16x32_bf16 v[40:43], v[234:237], v[124:127], v[40:43]
	ds_read_b128 v[234:237], v15 offset:256
	s_waitcnt lgkmcnt(7)
	v_mfma_f32_16x16x32_bf16 v[44:47], v[238:241], v[124:127], v[44:47]
	ds_read_b128 v[238:241], v15 offset:8704
	s_waitcnt lgkmcnt(7)
	v_mfma_f32_16x16x32_bf16 v[48:51], v[242:245], v[124:127], v[48:51]
	ds_read_b128 v[242:245], v15 offset:17152
	s_waitcnt lgkmcnt(7)
	v_mfma_f32_16x16x32_bf16 v[32:35], v[246:249], v[128:131], v[32:35]
	ds_read_b128 v[246:249], v15 offset:25600
	s_waitcnt lgkmcnt(7)
	v_mfma_f32_16x16x32_bf16 v[36:39], v[200:203], v[128:131], v[36:39]
	ds_read_b128 v[200:203], v15 offset:34048
	s_waitcnt lgkmcnt(7)
	v_mfma_f32_16x16x32_bf16 v[40:43], v[204:207], v[128:131], v[40:43]
	ds_read_b128 v[204:207], v15 offset:320
	s_waitcnt lgkmcnt(7)
	v_mfma_f32_16x16x32_bf16 v[44:47], v[208:211], v[128:131], v[44:47]
	ds_read_b128 v[208:211], v15 offset:8768
	s_waitcnt lgkmcnt(7)
	v_mfma_f32_16x16x32_bf16 v[48:51], v[212:215], v[128:131], v[48:51]
	ds_read_b128 v[212:215], v15 offset:17216
	s_waitcnt lgkmcnt(7)
	v_mfma_f32_16x16x32_bf16 v[32:35], v[234:237], v[132:135], v[32:35]
	ds_read_b128 v[234:237], v15 offset:25664
	s_waitcnt lgkmcnt(7)
	v_mfma_f32_16x16x32_bf16 v[36:39], v[238:241], v[132:135], v[36:39]
	ds_read_b128 v[238:241], v15 offset:34112
	s_waitcnt lgkmcnt(7)
	v_mfma_f32_16x16x32_bf16 v[40:43], v[242:245], v[132:135], v[40:43]
	ds_read_b128 v[242:245], v15 offset:384
	s_waitcnt lgkmcnt(7)
	v_mfma_f32_16x16x32_bf16 v[44:47], v[246:249], v[132:135], v[44:47]
	ds_read_b128 v[246:249], v15 offset:8832
	s_waitcnt lgkmcnt(7)
	v_mfma_f32_16x16x32_bf16 v[48:51], v[200:203], v[132:135], v[48:51]
	ds_read_b128 v[200:203], v15 offset:17280
	s_waitcnt lgkmcnt(7)
	v_mfma_f32_16x16x32_bf16 v[32:35], v[204:207], v[136:139], v[32:35]
	ds_read_b128 v[204:207], v15 offset:25728
	s_waitcnt lgkmcnt(7)
	v_mfma_f32_16x16x32_bf16 v[36:39], v[208:211], v[136:139], v[36:39]
	ds_read_b128 v[208:211], v15 offset:34176
	s_waitcnt lgkmcnt(7)
	v_mfma_f32_16x16x32_bf16 v[40:43], v[212:215], v[136:139], v[40:43]
	ds_read_b128 v[212:215], v15 offset:448
	s_waitcnt lgkmcnt(7)
	v_mfma_f32_16x16x32_bf16 v[44:47], v[234:237], v[136:139], v[44:47]
	ds_read_b128 v[234:237], v15 offset:8896
	s_waitcnt lgkmcnt(7)
	v_mfma_f32_16x16x32_bf16 v[48:51], v[238:241], v[136:139], v[48:51]
	ds_read_b128 v[238:241], v15 offset:17344
	s_waitcnt lgkmcnt(7)
	v_mfma_f32_16x16x32_bf16 v[32:35], v[242:245], v[140:143], v[32:35]
	ds_read_b128 v[242:245], v15 offset:25792
	s_waitcnt lgkmcnt(7)
	v_mfma_f32_16x16x32_bf16 v[36:39], v[246:249], v[140:143], v[36:39]
	ds_read_b128 v[246:249], v15 offset:34240
	s_waitcnt lgkmcnt(7)
	v_mfma_f32_16x16x32_bf16 v[40:43], v[200:203], v[140:143], v[40:43]
	s_waitcnt lgkmcnt(6)
	v_mfma_f32_16x16x32_bf16 v[44:47], v[204:207], v[140:143], v[44:47]
	s_waitcnt lgkmcnt(5)
	v_mfma_f32_16x16x32_bf16 v[48:51], v[208:211], v[140:143], v[48:51]
	s_waitcnt lgkmcnt(4)
	v_mfma_f32_16x16x32_bf16 v[32:35], v[212:215], v[144:147], v[32:35]
	s_waitcnt lgkmcnt(3)
	v_mfma_f32_16x16x32_bf16 v[36:39], v[234:237], v[144:147], v[36:39]
	s_waitcnt lgkmcnt(2)
	v_mfma_f32_16x16x32_bf16 v[40:43], v[238:241], v[144:147], v[40:43]
	s_waitcnt lgkmcnt(1)
	v_mfma_f32_16x16x32_bf16 v[44:47], v[242:245], v[144:147], v[44:47]
	s_waitcnt lgkmcnt(0)
	v_mfma_f32_16x16x32_bf16 v[48:51], v[246:249], v[144:147], v[48:51]
	s_waitcnt vmcnt(21)
	ds_write_b128 v6, v[172:175]
	ds_write_b128 v6, v[176:179] offset:8448
	ds_write_b128 v6, v[180:183] offset:16896
	ds_write_b128 v6, v[184:187] offset:25344
	ds_write_b128 v6, v[196:199] offset:33792
	s_waitcnt lgkmcnt(0)
	s_barrier
	global_load_dwordx4 v[172:175], v5, s[18:19] offset:2560
	global_load_dwordx4 v[176:179], v5, s[28:29] offset:2560
	global_load_dwordx4 v[180:183], v5, s[30:31] offset:2560
	global_load_dwordx4 v[184:187], v5, s[34:35] offset:2560
	global_load_dwordx4 v[196:199], v5, s[36:37] offset:2560
	global_load_dwordx4 v[116:119], v1, s[8:9] offset:2560
	global_load_dwordx4 v[120:123], v1, s[8:9] offset:2624
	global_load_dwordx4 v[124:127], v1, s[8:9] offset:2688
	global_load_dwordx4 v[128:131], v1, s[8:9] offset:2752
	global_load_dwordx4 v[132:135], v1, s[8:9] offset:2816
	global_load_dwordx4 v[136:139], v1, s[8:9] offset:2880
	global_load_dwordx4 v[140:143], v1, s[8:9] offset:2944
	global_load_dwordx4 v[144:147], v1, s[8:9] offset:3008
	s_waitcnt vmcnt(26)
	ds_read_b128 v[200:203], v8
	ds_read_b128 v[204:207], v8 offset:8448
	ds_read_b128 v[208:211], v8 offset:16896
	ds_read_b128 v[212:215], v8 offset:25344
	ds_read_b128 v[234:237], v8 offset:33792
	ds_read_b128 v[238:241], v8 offset:64
	ds_read_b128 v[242:245], v8 offset:8512
	ds_read_b128 v[246:249], v8 offset:16960
	s_waitcnt lgkmcnt(7)
	v_mfma_f32_16x16x32_bf16 v[32:35], v[200:203], v[52:55], v[32:35]
	ds_read_b128 v[200:203], v8 offset:25408
	s_waitcnt lgkmcnt(7)
	v_mfma_f32_16x16x32_bf16 v[36:39], v[204:207], v[52:55], v[36:39]
	ds_read_b128 v[204:207], v8 offset:33856
	s_waitcnt lgkmcnt(7)
	v_mfma_f32_16x16x32_bf16 v[40:43], v[208:211], v[52:55], v[40:43]
	ds_read_b128 v[208:211], v8 offset:128
	s_waitcnt lgkmcnt(7)
	v_mfma_f32_16x16x32_bf16 v[44:47], v[212:215], v[52:55], v[44:47]
	ds_read_b128 v[212:215], v8 offset:8576
	s_waitcnt lgkmcnt(7)
	v_mfma_f32_16x16x32_bf16 v[48:51], v[234:237], v[52:55], v[48:51]
	ds_read_b128 v[234:237], v8 offset:17024
	s_waitcnt lgkmcnt(7)
	v_mfma_f32_16x16x32_bf16 v[32:35], v[238:241], v[56:59], v[32:35]
	ds_read_b128 v[238:241], v8 offset:25472
	s_waitcnt lgkmcnt(7)
	v_mfma_f32_16x16x32_bf16 v[36:39], v[242:245], v[56:59], v[36:39]
	ds_read_b128 v[242:245], v8 offset:33920
	s_waitcnt lgkmcnt(7)
	v_mfma_f32_16x16x32_bf16 v[40:43], v[246:249], v[56:59], v[40:43]
	ds_read_b128 v[246:249], v8 offset:192
	s_waitcnt lgkmcnt(7)
	v_mfma_f32_16x16x32_bf16 v[44:47], v[200:203], v[56:59], v[44:47]
	ds_read_b128 v[200:203], v8 offset:8640
	s_waitcnt lgkmcnt(7)
	v_mfma_f32_16x16x32_bf16 v[48:51], v[204:207], v[56:59], v[48:51]
	ds_read_b128 v[204:207], v8 offset:17088
	s_waitcnt lgkmcnt(7)
	v_mfma_f32_16x16x32_bf16 v[32:35], v[208:211], v[60:63], v[32:35]
	ds_read_b128 v[208:211], v8 offset:25536
	s_waitcnt lgkmcnt(7)
	v_mfma_f32_16x16x32_bf16 v[36:39], v[212:215], v[60:63], v[36:39]
	ds_read_b128 v[212:215], v8 offset:33984
	s_waitcnt lgkmcnt(7)
	v_mfma_f32_16x16x32_bf16 v[40:43], v[234:237], v[60:63], v[40:43]
	ds_read_b128 v[234:237], v8 offset:256
	s_waitcnt lgkmcnt(7)
	v_mfma_f32_16x16x32_bf16 v[44:47], v[238:241], v[60:63], v[44:47]
	ds_read_b128 v[238:241], v8 offset:8704
	s_waitcnt lgkmcnt(7)
	v_mfma_f32_16x16x32_bf16 v[48:51], v[242:245], v[60:63], v[48:51]
	ds_read_b128 v[242:245], v8 offset:17152
	s_waitcnt lgkmcnt(7)
	v_mfma_f32_16x16x32_bf16 v[32:35], v[246:249], v[64:67], v[32:35]
	ds_read_b128 v[246:249], v8 offset:25600
	s_waitcnt lgkmcnt(7)
	v_mfma_f32_16x16x32_bf16 v[36:39], v[200:203], v[64:67], v[36:39]
	ds_read_b128 v[200:203], v8 offset:34048
	s_waitcnt lgkmcnt(7)
	v_mfma_f32_16x16x32_bf16 v[40:43], v[204:207], v[64:67], v[40:43]
	ds_read_b128 v[204:207], v8 offset:320
	s_waitcnt lgkmcnt(7)
	v_mfma_f32_16x16x32_bf16 v[44:47], v[208:211], v[64:67], v[44:47]
	ds_read_b128 v[208:211], v8 offset:8768
	s_waitcnt lgkmcnt(7)
	v_mfma_f32_16x16x32_bf16 v[48:51], v[212:215], v[64:67], v[48:51]
	ds_read_b128 v[212:215], v8 offset:17216
	s_waitcnt lgkmcnt(7)
	v_mfma_f32_16x16x32_bf16 v[32:35], v[234:237], v[68:71], v[32:35]
	ds_read_b128 v[234:237], v8 offset:25664
	s_waitcnt lgkmcnt(7)
	v_mfma_f32_16x16x32_bf16 v[36:39], v[238:241], v[68:71], v[36:39]
	ds_read_b128 v[238:241], v8 offset:34112
	s_waitcnt lgkmcnt(7)
	v_mfma_f32_16x16x32_bf16 v[40:43], v[242:245], v[68:71], v[40:43]
	ds_read_b128 v[242:245], v8 offset:384
	s_waitcnt lgkmcnt(7)
	v_mfma_f32_16x16x32_bf16 v[44:47], v[246:249], v[68:71], v[44:47]
	ds_read_b128 v[246:249], v8 offset:8832
	s_waitcnt lgkmcnt(7)
	v_mfma_f32_16x16x32_bf16 v[48:51], v[200:203], v[68:71], v[48:51]
	ds_read_b128 v[200:203], v8 offset:17280
	s_waitcnt lgkmcnt(7)
	v_mfma_f32_16x16x32_bf16 v[32:35], v[204:207], v[72:75], v[32:35]
	ds_read_b128 v[204:207], v8 offset:25728
	s_waitcnt lgkmcnt(7)
	v_mfma_f32_16x16x32_bf16 v[36:39], v[208:211], v[72:75], v[36:39]
	ds_read_b128 v[208:211], v8 offset:34176
	s_waitcnt lgkmcnt(7)
	v_mfma_f32_16x16x32_bf16 v[40:43], v[212:215], v[72:75], v[40:43]
	ds_read_b128 v[212:215], v8 offset:448
	s_waitcnt lgkmcnt(7)
	v_mfma_f32_16x16x32_bf16 v[44:47], v[234:237], v[72:75], v[44:47]
	ds_read_b128 v[234:237], v8 offset:8896
	s_waitcnt lgkmcnt(7)
	v_mfma_f32_16x16x32_bf16 v[48:51], v[238:241], v[72:75], v[48:51]
	ds_read_b128 v[238:241], v8 offset:17344
	s_waitcnt lgkmcnt(7)
	v_mfma_f32_16x16x32_bf16 v[32:35], v[242:245], v[76:79], v[32:35]
	ds_read_b128 v[242:245], v8 offset:25792
	s_waitcnt lgkmcnt(7)
	v_mfma_f32_16x16x32_bf16 v[36:39], v[246:249], v[76:79], v[36:39]
	ds_read_b128 v[246:249], v8 offset:34240
	s_waitcnt lgkmcnt(7)
	v_mfma_f32_16x16x32_bf16 v[40:43], v[200:203], v[76:79], v[40:43]
	s_waitcnt lgkmcnt(6)
	v_mfma_f32_16x16x32_bf16 v[44:47], v[204:207], v[76:79], v[44:47]
	s_waitcnt lgkmcnt(5)
	v_mfma_f32_16x16x32_bf16 v[48:51], v[208:211], v[76:79], v[48:51]
	s_waitcnt lgkmcnt(4)
	v_mfma_f32_16x16x32_bf16 v[32:35], v[212:215], v[80:83], v[32:35]
	s_waitcnt lgkmcnt(3)
	v_mfma_f32_16x16x32_bf16 v[36:39], v[234:237], v[80:83], v[36:39]
	s_waitcnt lgkmcnt(2)
	v_mfma_f32_16x16x32_bf16 v[40:43], v[238:241], v[80:83], v[40:43]
	s_waitcnt lgkmcnt(1)
	v_mfma_f32_16x16x32_bf16 v[44:47], v[242:245], v[80:83], v[44:47]
	s_waitcnt lgkmcnt(0)
	v_mfma_f32_16x16x32_bf16 v[48:51], v[246:249], v[80:83], v[48:51]
	s_waitcnt vmcnt(21)
	ds_write_b128 v7, v[148:151]
	ds_write_b128 v7, v[152:155] offset:8448
	ds_write_b128 v7, v[156:159] offset:16896
	ds_write_b128 v7, v[22:25] offset:25344
	ds_write_b128 v7, v[26:29] offset:33792
	s_waitcnt lgkmcnt(0)
	s_barrier
	global_load_dwordx4 v[148:151], v5, s[18:19] offset:3072
	global_load_dwordx4 v[152:155], v5, s[28:29] offset:3072
	global_load_dwordx4 v[156:159], v5, s[30:31] offset:3072
	global_load_dwordx4 v[22:25], v5, s[34:35] offset:3072
	global_load_dwordx4 v[26:29], v5, s[36:37] offset:3072
	global_load_dwordx4 v[52:55], v1, s[8:9] offset:3072
	global_load_dwordx4 v[56:59], v1, s[8:9] offset:3136
	global_load_dwordx4 v[60:63], v1, s[8:9] offset:3200
	global_load_dwordx4 v[64:67], v1, s[8:9] offset:3264
	global_load_dwordx4 v[68:71], v1, s[8:9] offset:3328
	global_load_dwordx4 v[72:75], v1, s[8:9] offset:3392
	global_load_dwordx4 v[76:79], v1, s[8:9] offset:3456
	global_load_dwordx4 v[80:83], v1, s[8:9] offset:3520
	s_waitcnt vmcnt(26)
	ds_read_b128 v[200:203], v9
	ds_read_b128 v[204:207], v9 offset:8448
	ds_read_b128 v[208:211], v9 offset:16896
	ds_read_b128 v[212:215], v9 offset:25344
	ds_read_b128 v[234:237], v9 offset:33792
	ds_read_b128 v[238:241], v9 offset:64
	ds_read_b128 v[242:245], v9 offset:8512
	ds_read_b128 v[246:249], v9 offset:16960
	s_waitcnt lgkmcnt(7)
	v_mfma_f32_16x16x32_bf16 v[32:35], v[200:203], v[84:87], v[32:35]
	ds_read_b128 v[200:203], v9 offset:25408
	s_waitcnt lgkmcnt(7)
	v_mfma_f32_16x16x32_bf16 v[36:39], v[204:207], v[84:87], v[36:39]
	ds_read_b128 v[204:207], v9 offset:33856
	s_waitcnt lgkmcnt(7)
	v_mfma_f32_16x16x32_bf16 v[40:43], v[208:211], v[84:87], v[40:43]
	ds_read_b128 v[208:211], v9 offset:128
	s_waitcnt lgkmcnt(7)
	v_mfma_f32_16x16x32_bf16 v[44:47], v[212:215], v[84:87], v[44:47]
	ds_read_b128 v[212:215], v9 offset:8576
	s_waitcnt lgkmcnt(7)
	v_mfma_f32_16x16x32_bf16 v[48:51], v[234:237], v[84:87], v[48:51]
	ds_read_b128 v[234:237], v9 offset:17024
	s_waitcnt lgkmcnt(7)
	v_mfma_f32_16x16x32_bf16 v[32:35], v[238:241], v[88:91], v[32:35]
	ds_read_b128 v[238:241], v9 offset:25472
	s_waitcnt lgkmcnt(7)
	v_mfma_f32_16x16x32_bf16 v[36:39], v[242:245], v[88:91], v[36:39]
	ds_read_b128 v[242:245], v9 offset:33920
	s_waitcnt lgkmcnt(7)
	v_mfma_f32_16x16x32_bf16 v[40:43], v[246:249], v[88:91], v[40:43]
	ds_read_b128 v[246:249], v9 offset:192
	s_waitcnt lgkmcnt(7)
	v_mfma_f32_16x16x32_bf16 v[44:47], v[200:203], v[88:91], v[44:47]
	ds_read_b128 v[200:203], v9 offset:8640
	s_waitcnt lgkmcnt(7)
	v_mfma_f32_16x16x32_bf16 v[48:51], v[204:207], v[88:91], v[48:51]
	ds_read_b128 v[204:207], v9 offset:17088
	s_waitcnt lgkmcnt(7)
	v_mfma_f32_16x16x32_bf16 v[32:35], v[208:211], v[92:95], v[32:35]
	ds_read_b128 v[208:211], v9 offset:25536
	s_waitcnt lgkmcnt(7)
	v_mfma_f32_16x16x32_bf16 v[36:39], v[212:215], v[92:95], v[36:39]
	ds_read_b128 v[212:215], v9 offset:33984
	s_waitcnt lgkmcnt(7)
	v_mfma_f32_16x16x32_bf16 v[40:43], v[234:237], v[92:95], v[40:43]
	ds_read_b128 v[234:237], v9 offset:256
	s_waitcnt lgkmcnt(7)
	v_mfma_f32_16x16x32_bf16 v[44:47], v[238:241], v[92:95], v[44:47]
	ds_read_b128 v[238:241], v9 offset:8704
	s_waitcnt lgkmcnt(7)
	v_mfma_f32_16x16x32_bf16 v[48:51], v[242:245], v[92:95], v[48:51]
	ds_read_b128 v[242:245], v9 offset:17152
	s_waitcnt lgkmcnt(7)
	v_mfma_f32_16x16x32_bf16 v[32:35], v[246:249], v[96:99], v[32:35]
	ds_read_b128 v[246:249], v9 offset:25600
	s_waitcnt lgkmcnt(7)
	v_mfma_f32_16x16x32_bf16 v[36:39], v[200:203], v[96:99], v[36:39]
	ds_read_b128 v[200:203], v9 offset:34048
	s_waitcnt lgkmcnt(7)
	v_mfma_f32_16x16x32_bf16 v[40:43], v[204:207], v[96:99], v[40:43]
	ds_read_b128 v[204:207], v9 offset:320
	s_waitcnt lgkmcnt(7)
	v_mfma_f32_16x16x32_bf16 v[44:47], v[208:211], v[96:99], v[44:47]
	ds_read_b128 v[208:211], v9 offset:8768
	s_waitcnt lgkmcnt(7)
	v_mfma_f32_16x16x32_bf16 v[48:51], v[212:215], v[96:99], v[48:51]
	ds_read_b128 v[212:215], v9 offset:17216
	s_waitcnt lgkmcnt(7)
	v_mfma_f32_16x16x32_bf16 v[32:35], v[234:237], v[100:103], v[32:35]
	ds_read_b128 v[234:237], v9 offset:25664
	s_waitcnt lgkmcnt(7)
	v_mfma_f32_16x16x32_bf16 v[36:39], v[238:241], v[100:103], v[36:39]
	ds_read_b128 v[238:241], v9 offset:34112
	s_waitcnt lgkmcnt(7)
	v_mfma_f32_16x16x32_bf16 v[40:43], v[242:245], v[100:103], v[40:43]
	ds_read_b128 v[242:245], v9 offset:384
	s_waitcnt lgkmcnt(7)
	v_mfma_f32_16x16x32_bf16 v[44:47], v[246:249], v[100:103], v[44:47]
	ds_read_b128 v[246:249], v9 offset:8832
	s_waitcnt lgkmcnt(7)
	v_mfma_f32_16x16x32_bf16 v[48:51], v[200:203], v[100:103], v[48:51]
	ds_read_b128 v[200:203], v9 offset:17280
	s_waitcnt lgkmcnt(7)
	v_mfma_f32_16x16x32_bf16 v[32:35], v[204:207], v[104:107], v[32:35]
	ds_read_b128 v[204:207], v9 offset:25728
	s_waitcnt lgkmcnt(7)
	v_mfma_f32_16x16x32_bf16 v[36:39], v[208:211], v[104:107], v[36:39]
	ds_read_b128 v[208:211], v9 offset:34176
	s_waitcnt lgkmcnt(7)
	v_mfma_f32_16x16x32_bf16 v[40:43], v[212:215], v[104:107], v[40:43]
	ds_read_b128 v[212:215], v9 offset:448
	s_waitcnt lgkmcnt(7)
	v_mfma_f32_16x16x32_bf16 v[44:47], v[234:237], v[104:107], v[44:47]
	ds_read_b128 v[234:237], v9 offset:8896
	s_waitcnt lgkmcnt(7)
	v_mfma_f32_16x16x32_bf16 v[48:51], v[238:241], v[104:107], v[48:51]
	ds_read_b128 v[238:241], v9 offset:17344
	s_waitcnt lgkmcnt(7)
	v_mfma_f32_16x16x32_bf16 v[32:35], v[242:245], v[108:111], v[32:35]
	ds_read_b128 v[242:245], v9 offset:25792
	s_waitcnt lgkmcnt(7)
	v_mfma_f32_16x16x32_bf16 v[36:39], v[246:249], v[108:111], v[36:39]
	ds_read_b128 v[246:249], v9 offset:34240
	s_waitcnt lgkmcnt(7)
	v_mfma_f32_16x16x32_bf16 v[40:43], v[200:203], v[108:111], v[40:43]
	s_waitcnt lgkmcnt(6)
	v_mfma_f32_16x16x32_bf16 v[44:47], v[204:207], v[108:111], v[44:47]
	s_waitcnt lgkmcnt(5)
	v_mfma_f32_16x16x32_bf16 v[48:51], v[208:211], v[108:111], v[48:51]
	s_waitcnt lgkmcnt(4)
	v_mfma_f32_16x16x32_bf16 v[32:35], v[212:215], v[112:115], v[32:35]
	s_waitcnt lgkmcnt(3)
	v_mfma_f32_16x16x32_bf16 v[36:39], v[234:237], v[112:115], v[36:39]
	s_waitcnt lgkmcnt(2)
	v_mfma_f32_16x16x32_bf16 v[40:43], v[238:241], v[112:115], v[40:43]
	s_waitcnt lgkmcnt(1)
	v_mfma_f32_16x16x32_bf16 v[44:47], v[242:245], v[112:115], v[44:47]
	s_waitcnt lgkmcnt(0)
	v_mfma_f32_16x16x32_bf16 v[48:51], v[246:249], v[112:115], v[48:51]
	s_waitcnt vmcnt(21)
	ds_write_b128 v14, v[172:175]
	ds_write_b128 v14, v[176:179] offset:8448
	ds_write_b128 v14, v[180:183] offset:16896
	ds_write_b128 v14, v[184:187] offset:25344
	ds_write_b128 v14, v[196:199] offset:33792
	s_waitcnt lgkmcnt(0)
	s_barrier
	global_load_dwordx4 v[172:175], v5, s[18:19] offset:3584
	global_load_dwordx4 v[176:179], v5, s[28:29] offset:3584
	global_load_dwordx4 v[180:183], v5, s[30:31] offset:3584
	global_load_dwordx4 v[184:187], v5, s[34:35] offset:3584
	global_load_dwordx4 v[196:199], v5, s[36:37] offset:3584
	global_load_dwordx4 v[84:87], v1, s[8:9] offset:3584
	global_load_dwordx4 v[88:91], v1, s[8:9] offset:3648
	global_load_dwordx4 v[92:95], v1, s[8:9] offset:3712
	global_load_dwordx4 v[96:99], v1, s[8:9] offset:3776
	global_load_dwordx4 v[100:103], v1, s[8:9] offset:3840
	global_load_dwordx4 v[104:107], v1, s[8:9] offset:3904
	global_load_dwordx4 v[108:111], v1, s[8:9] offset:3968
	global_load_dwordx4 v[112:115], v1, s[8:9] offset:4032
	s_waitcnt vmcnt(26)
	ds_read_b128 v[200:203], v15
	ds_read_b128 v[204:207], v15 offset:8448
	ds_read_b128 v[208:211], v15 offset:16896
	ds_read_b128 v[212:215], v15 offset:25344
	ds_read_b128 v[234:237], v15 offset:33792
	ds_read_b128 v[238:241], v15 offset:64
	ds_read_b128 v[242:245], v15 offset:8512
	ds_read_b128 v[246:249], v15 offset:16960
	s_waitcnt lgkmcnt(7)
	v_mfma_f32_16x16x32_bf16 v[32:35], v[200:203], v[116:119], v[32:35]
	ds_read_b128 v[200:203], v15 offset:25408
	s_waitcnt lgkmcnt(7)
	v_mfma_f32_16x16x32_bf16 v[36:39], v[204:207], v[116:119], v[36:39]
	ds_read_b128 v[204:207], v15 offset:33856
	s_waitcnt lgkmcnt(7)
	v_mfma_f32_16x16x32_bf16 v[40:43], v[208:211], v[116:119], v[40:43]
	ds_read_b128 v[208:211], v15 offset:128
	s_waitcnt lgkmcnt(7)
	v_mfma_f32_16x16x32_bf16 v[44:47], v[212:215], v[116:119], v[44:47]
	ds_read_b128 v[212:215], v15 offset:8576
	s_waitcnt lgkmcnt(7)
	v_mfma_f32_16x16x32_bf16 v[48:51], v[234:237], v[116:119], v[48:51]
	ds_read_b128 v[234:237], v15 offset:17024
	s_waitcnt lgkmcnt(7)
	v_mfma_f32_16x16x32_bf16 v[32:35], v[238:241], v[120:123], v[32:35]
	ds_read_b128 v[238:241], v15 offset:25472
	s_waitcnt lgkmcnt(7)
	v_mfma_f32_16x16x32_bf16 v[36:39], v[242:245], v[120:123], v[36:39]
	ds_read_b128 v[242:245], v15 offset:33920
	s_waitcnt lgkmcnt(7)
	v_mfma_f32_16x16x32_bf16 v[40:43], v[246:249], v[120:123], v[40:43]
	ds_read_b128 v[246:249], v15 offset:192
	s_waitcnt lgkmcnt(7)
	v_mfma_f32_16x16x32_bf16 v[44:47], v[200:203], v[120:123], v[44:47]
	ds_read_b128 v[200:203], v15 offset:8640
	s_waitcnt lgkmcnt(7)
	v_mfma_f32_16x16x32_bf16 v[48:51], v[204:207], v[120:123], v[48:51]
	ds_read_b128 v[204:207], v15 offset:17088
	s_waitcnt lgkmcnt(7)
	v_mfma_f32_16x16x32_bf16 v[32:35], v[208:211], v[124:127], v[32:35]
	ds_read_b128 v[208:211], v15 offset:25536
	s_waitcnt lgkmcnt(7)
	v_mfma_f32_16x16x32_bf16 v[36:39], v[212:215], v[124:127], v[36:39]
	ds_read_b128 v[212:215], v15 offset:33984
	s_waitcnt lgkmcnt(7)
	v_mfma_f32_16x16x32_bf16 v[40:43], v[234:237], v[124:127], v[40:43]
	ds_read_b128 v[234:237], v15 offset:256
	s_waitcnt lgkmcnt(7)
	v_mfma_f32_16x16x32_bf16 v[44:47], v[238:241], v[124:127], v[44:47]
	ds_read_b128 v[238:241], v15 offset:8704
	s_waitcnt lgkmcnt(7)
	v_mfma_f32_16x16x32_bf16 v[48:51], v[242:245], v[124:127], v[48:51]
	ds_read_b128 v[242:245], v15 offset:17152
	s_waitcnt lgkmcnt(7)
	v_mfma_f32_16x16x32_bf16 v[32:35], v[246:249], v[128:131], v[32:35]
	ds_read_b128 v[246:249], v15 offset:25600
	s_waitcnt lgkmcnt(7)
	v_mfma_f32_16x16x32_bf16 v[36:39], v[200:203], v[128:131], v[36:39]
	ds_read_b128 v[200:203], v15 offset:34048
	s_waitcnt lgkmcnt(7)
	v_mfma_f32_16x16x32_bf16 v[40:43], v[204:207], v[128:131], v[40:43]
	ds_read_b128 v[204:207], v15 offset:320
	s_waitcnt lgkmcnt(7)
	v_mfma_f32_16x16x32_bf16 v[44:47], v[208:211], v[128:131], v[44:47]
	ds_read_b128 v[208:211], v15 offset:8768
	s_waitcnt lgkmcnt(7)
	v_mfma_f32_16x16x32_bf16 v[48:51], v[212:215], v[128:131], v[48:51]
	ds_read_b128 v[212:215], v15 offset:17216
	s_waitcnt lgkmcnt(7)
	v_mfma_f32_16x16x32_bf16 v[32:35], v[234:237], v[132:135], v[32:35]
	ds_read_b128 v[234:237], v15 offset:25664
	s_waitcnt lgkmcnt(7)
	v_mfma_f32_16x16x32_bf16 v[36:39], v[238:241], v[132:135], v[36:39]
	ds_read_b128 v[238:241], v15 offset:34112
	s_waitcnt lgkmcnt(7)
	v_mfma_f32_16x16x32_bf16 v[40:43], v[242:245], v[132:135], v[40:43]
	ds_read_b128 v[242:245], v15 offset:384
	s_waitcnt lgkmcnt(7)
	v_mfma_f32_16x16x32_bf16 v[44:47], v[246:249], v[132:135], v[44:47]
	ds_read_b128 v[246:249], v15 offset:8832
	s_waitcnt lgkmcnt(7)
	v_mfma_f32_16x16x32_bf16 v[48:51], v[200:203], v[132:135], v[48:51]
	ds_read_b128 v[200:203], v15 offset:17280
	s_waitcnt lgkmcnt(7)
	v_mfma_f32_16x16x32_bf16 v[32:35], v[204:207], v[136:139], v[32:35]
	ds_read_b128 v[204:207], v15 offset:25728
	s_waitcnt lgkmcnt(7)
	v_mfma_f32_16x16x32_bf16 v[36:39], v[208:211], v[136:139], v[36:39]
	ds_read_b128 v[208:211], v15 offset:34176
	s_waitcnt lgkmcnt(7)
	v_mfma_f32_16x16x32_bf16 v[40:43], v[212:215], v[136:139], v[40:43]
	ds_read_b128 v[212:215], v15 offset:448
	s_waitcnt lgkmcnt(7)
	v_mfma_f32_16x16x32_bf16 v[44:47], v[234:237], v[136:139], v[44:47]
	ds_read_b128 v[234:237], v15 offset:8896
	s_waitcnt lgkmcnt(7)
	v_mfma_f32_16x16x32_bf16 v[48:51], v[238:241], v[136:139], v[48:51]
	ds_read_b128 v[238:241], v15 offset:17344
	s_waitcnt lgkmcnt(7)
	v_mfma_f32_16x16x32_bf16 v[32:35], v[242:245], v[140:143], v[32:35]
	ds_read_b128 v[242:245], v15 offset:25792
	s_waitcnt lgkmcnt(7)
	v_mfma_f32_16x16x32_bf16 v[36:39], v[246:249], v[140:143], v[36:39]
	ds_read_b128 v[246:249], v15 offset:34240
	s_waitcnt lgkmcnt(7)
	v_mfma_f32_16x16x32_bf16 v[40:43], v[200:203], v[140:143], v[40:43]
	s_waitcnt lgkmcnt(6)
	v_mfma_f32_16x16x32_bf16 v[44:47], v[204:207], v[140:143], v[44:47]
	s_waitcnt lgkmcnt(5)
	v_mfma_f32_16x16x32_bf16 v[48:51], v[208:211], v[140:143], v[48:51]
	s_waitcnt lgkmcnt(4)
	v_mfma_f32_16x16x32_bf16 v[32:35], v[212:215], v[144:147], v[32:35]
	s_waitcnt lgkmcnt(3)
	v_mfma_f32_16x16x32_bf16 v[36:39], v[234:237], v[144:147], v[36:39]
	s_waitcnt lgkmcnt(2)
	v_mfma_f32_16x16x32_bf16 v[40:43], v[238:241], v[144:147], v[40:43]
	s_waitcnt lgkmcnt(1)
	v_mfma_f32_16x16x32_bf16 v[44:47], v[242:245], v[144:147], v[44:47]
	s_waitcnt lgkmcnt(0)
	v_mfma_f32_16x16x32_bf16 v[48:51], v[246:249], v[144:147], v[48:51]
	s_waitcnt vmcnt(21)
	ds_write_b128 v6, v[148:151]
	ds_write_b128 v6, v[152:155] offset:8448
	ds_write_b128 v6, v[156:159] offset:16896
	ds_write_b128 v6, v[22:25] offset:25344
	ds_write_b128 v6, v[26:29] offset:33792
	s_waitcnt lgkmcnt(0)
	s_barrier
	s_waitcnt vmcnt(13)
	ds_read_b128 v[200:203], v8
	ds_read_b128 v[204:207], v8 offset:8448
	ds_read_b128 v[208:211], v8 offset:16896
	ds_read_b128 v[212:215], v8 offset:25344
	ds_read_b128 v[234:237], v8 offset:33792
	ds_read_b128 v[238:241], v8 offset:64
	ds_read_b128 v[242:245], v8 offset:8512
	ds_read_b128 v[246:249], v8 offset:16960
	s_waitcnt lgkmcnt(7)
	v_mfma_f32_16x16x32_bf16 v[32:35], v[200:203], v[52:55], v[32:35]
	ds_read_b128 v[200:203], v8 offset:25408
	s_waitcnt lgkmcnt(7)
	v_mfma_f32_16x16x32_bf16 v[36:39], v[204:207], v[52:55], v[36:39]
	ds_read_b128 v[204:207], v8 offset:33856
	s_waitcnt lgkmcnt(7)
	v_mfma_f32_16x16x32_bf16 v[40:43], v[208:211], v[52:55], v[40:43]
	ds_read_b128 v[208:211], v8 offset:128
	s_waitcnt lgkmcnt(7)
	v_mfma_f32_16x16x32_bf16 v[44:47], v[212:215], v[52:55], v[44:47]
	ds_read_b128 v[212:215], v8 offset:8576
	s_waitcnt lgkmcnt(7)
	v_mfma_f32_16x16x32_bf16 v[48:51], v[234:237], v[52:55], v[48:51]
	ds_read_b128 v[234:237], v8 offset:17024
	s_waitcnt lgkmcnt(7)
	v_mfma_f32_16x16x32_bf16 v[32:35], v[238:241], v[56:59], v[32:35]
	ds_read_b128 v[238:241], v8 offset:25472
	s_waitcnt lgkmcnt(7)
	v_mfma_f32_16x16x32_bf16 v[36:39], v[242:245], v[56:59], v[36:39]
	ds_read_b128 v[242:245], v8 offset:33920
	s_waitcnt lgkmcnt(7)
	v_mfma_f32_16x16x32_bf16 v[40:43], v[246:249], v[56:59], v[40:43]
	ds_read_b128 v[246:249], v8 offset:192
	s_waitcnt lgkmcnt(7)
	v_mfma_f32_16x16x32_bf16 v[44:47], v[200:203], v[56:59], v[44:47]
	ds_read_b128 v[200:203], v8 offset:8640
	s_waitcnt lgkmcnt(7)
	v_mfma_f32_16x16x32_bf16 v[48:51], v[204:207], v[56:59], v[48:51]
	ds_read_b128 v[204:207], v8 offset:17088
	s_waitcnt lgkmcnt(7)
	v_mfma_f32_16x16x32_bf16 v[32:35], v[208:211], v[60:63], v[32:35]
	ds_read_b128 v[208:211], v8 offset:25536
	s_waitcnt lgkmcnt(7)
	v_mfma_f32_16x16x32_bf16 v[36:39], v[212:215], v[60:63], v[36:39]
	ds_read_b128 v[212:215], v8 offset:33984
	s_waitcnt lgkmcnt(7)
	v_mfma_f32_16x16x32_bf16 v[40:43], v[234:237], v[60:63], v[40:43]
	ds_read_b128 v[234:237], v8 offset:256
	s_waitcnt lgkmcnt(7)
	v_mfma_f32_16x16x32_bf16 v[44:47], v[238:241], v[60:63], v[44:47]
	ds_read_b128 v[238:241], v8 offset:8704
	s_waitcnt lgkmcnt(7)
	v_mfma_f32_16x16x32_bf16 v[48:51], v[242:245], v[60:63], v[48:51]
	ds_read_b128 v[242:245], v8 offset:17152
	s_waitcnt lgkmcnt(7)
	v_mfma_f32_16x16x32_bf16 v[32:35], v[246:249], v[64:67], v[32:35]
	ds_read_b128 v[246:249], v8 offset:25600
	s_waitcnt lgkmcnt(7)
	v_mfma_f32_16x16x32_bf16 v[36:39], v[200:203], v[64:67], v[36:39]
	ds_read_b128 v[200:203], v8 offset:34048
	s_waitcnt lgkmcnt(7)
	v_mfma_f32_16x16x32_bf16 v[40:43], v[204:207], v[64:67], v[40:43]
	ds_read_b128 v[204:207], v8 offset:320
	s_waitcnt lgkmcnt(7)
	v_mfma_f32_16x16x32_bf16 v[44:47], v[208:211], v[64:67], v[44:47]
	ds_read_b128 v[208:211], v8 offset:8768
	s_waitcnt lgkmcnt(7)
	v_mfma_f32_16x16x32_bf16 v[48:51], v[212:215], v[64:67], v[48:51]
	ds_read_b128 v[212:215], v8 offset:17216
	s_waitcnt lgkmcnt(7)
	v_mfma_f32_16x16x32_bf16 v[32:35], v[234:237], v[68:71], v[32:35]
	ds_read_b128 v[234:237], v8 offset:25664
	s_waitcnt lgkmcnt(7)
	v_mfma_f32_16x16x32_bf16 v[36:39], v[238:241], v[68:71], v[36:39]
	ds_read_b128 v[238:241], v8 offset:34112
	s_waitcnt lgkmcnt(7)
	v_mfma_f32_16x16x32_bf16 v[40:43], v[242:245], v[68:71], v[40:43]
	ds_read_b128 v[242:245], v8 offset:384
	s_waitcnt lgkmcnt(7)
	v_mfma_f32_16x16x32_bf16 v[44:47], v[246:249], v[68:71], v[44:47]
	ds_read_b128 v[246:249], v8 offset:8832
	s_waitcnt lgkmcnt(7)
	v_mfma_f32_16x16x32_bf16 v[48:51], v[200:203], v[68:71], v[48:51]
	ds_read_b128 v[200:203], v8 offset:17280
	s_waitcnt lgkmcnt(7)
	v_mfma_f32_16x16x32_bf16 v[32:35], v[204:207], v[72:75], v[32:35]
	ds_read_b128 v[204:207], v8 offset:25728
	s_waitcnt lgkmcnt(7)
	v_mfma_f32_16x16x32_bf16 v[36:39], v[208:211], v[72:75], v[36:39]
	ds_read_b128 v[208:211], v8 offset:34176
	s_waitcnt lgkmcnt(7)
	v_mfma_f32_16x16x32_bf16 v[40:43], v[212:215], v[72:75], v[40:43]
	ds_read_b128 v[212:215], v8 offset:448
	s_waitcnt lgkmcnt(7)
	v_mfma_f32_16x16x32_bf16 v[44:47], v[234:237], v[72:75], v[44:47]
	ds_read_b128 v[234:237], v8 offset:8896
	s_waitcnt lgkmcnt(7)
	v_mfma_f32_16x16x32_bf16 v[48:51], v[238:241], v[72:75], v[48:51]
	ds_read_b128 v[238:241], v8 offset:17344
	s_waitcnt lgkmcnt(7)
	v_mfma_f32_16x16x32_bf16 v[32:35], v[242:245], v[76:79], v[32:35]
	ds_read_b128 v[242:245], v8 offset:25792
	s_waitcnt lgkmcnt(7)
	v_mfma_f32_16x16x32_bf16 v[36:39], v[246:249], v[76:79], v[36:39]
	ds_read_b128 v[246:249], v8 offset:34240
	s_waitcnt lgkmcnt(7)
	v_mfma_f32_16x16x32_bf16 v[40:43], v[200:203], v[76:79], v[40:43]
	s_waitcnt lgkmcnt(6)
	v_mfma_f32_16x16x32_bf16 v[44:47], v[204:207], v[76:79], v[44:47]
	s_waitcnt lgkmcnt(5)
	v_mfma_f32_16x16x32_bf16 v[48:51], v[208:211], v[76:79], v[48:51]
	s_waitcnt lgkmcnt(4)
	v_mfma_f32_16x16x32_bf16 v[32:35], v[212:215], v[80:83], v[32:35]
	s_waitcnt lgkmcnt(3)
	v_mfma_f32_16x16x32_bf16 v[36:39], v[234:237], v[80:83], v[36:39]
	s_waitcnt lgkmcnt(2)
	v_mfma_f32_16x16x32_bf16 v[40:43], v[238:241], v[80:83], v[40:43]
	s_waitcnt lgkmcnt(1)
	v_mfma_f32_16x16x32_bf16 v[44:47], v[242:245], v[80:83], v[44:47]
	s_waitcnt lgkmcnt(0)
	v_mfma_f32_16x16x32_bf16 v[48:51], v[246:249], v[80:83], v[48:51]
	s_waitcnt vmcnt(8)
	ds_write_b128 v7, v[172:175]
	ds_write_b128 v7, v[176:179] offset:8448
	ds_write_b128 v7, v[180:183] offset:16896
	ds_write_b128 v7, v[184:187] offset:25344
	ds_write_b128 v7, v[196:199] offset:33792
	s_waitcnt lgkmcnt(0)
	s_barrier
	s_waitcnt vmcnt(0)
	ds_read_b128 v[200:203], v9
	ds_read_b128 v[204:207], v9 offset:8448
	ds_read_b128 v[208:211], v9 offset:16896
	ds_read_b128 v[212:215], v9 offset:25344
	ds_read_b128 v[234:237], v9 offset:33792
	ds_read_b128 v[238:241], v9 offset:64
	ds_read_b128 v[242:245], v9 offset:8512
	ds_read_b128 v[246:249], v9 offset:16960
	s_waitcnt lgkmcnt(7)
	v_mfma_f32_16x16x32_bf16 v[32:35], v[200:203], v[84:87], v[32:35]
	ds_read_b128 v[200:203], v9 offset:25408
	s_waitcnt lgkmcnt(7)
	v_mfma_f32_16x16x32_bf16 v[36:39], v[204:207], v[84:87], v[36:39]
	ds_read_b128 v[204:207], v9 offset:33856
	s_waitcnt lgkmcnt(7)
	v_mfma_f32_16x16x32_bf16 v[40:43], v[208:211], v[84:87], v[40:43]
	ds_read_b128 v[208:211], v9 offset:128
	s_waitcnt lgkmcnt(7)
	v_mfma_f32_16x16x32_bf16 v[44:47], v[212:215], v[84:87], v[44:47]
	ds_read_b128 v[212:215], v9 offset:8576
	s_waitcnt lgkmcnt(7)
	v_mfma_f32_16x16x32_bf16 v[48:51], v[234:237], v[84:87], v[48:51]
	ds_read_b128 v[234:237], v9 offset:17024
	s_waitcnt lgkmcnt(7)
	v_mfma_f32_16x16x32_bf16 v[32:35], v[238:241], v[88:91], v[32:35]
	ds_read_b128 v[238:241], v9 offset:25472
	s_waitcnt lgkmcnt(7)
	v_mfma_f32_16x16x32_bf16 v[36:39], v[242:245], v[88:91], v[36:39]
	ds_read_b128 v[242:245], v9 offset:33920
	s_waitcnt lgkmcnt(7)
	v_mfma_f32_16x16x32_bf16 v[40:43], v[246:249], v[88:91], v[40:43]
	ds_read_b128 v[246:249], v9 offset:192
	s_waitcnt lgkmcnt(7)
	v_mfma_f32_16x16x32_bf16 v[44:47], v[200:203], v[88:91], v[44:47]
	ds_read_b128 v[200:203], v9 offset:8640
	s_waitcnt lgkmcnt(7)
	v_mfma_f32_16x16x32_bf16 v[48:51], v[204:207], v[88:91], v[48:51]
	ds_read_b128 v[204:207], v9 offset:17088
	s_waitcnt lgkmcnt(7)
	v_mfma_f32_16x16x32_bf16 v[32:35], v[208:211], v[92:95], v[32:35]
	ds_read_b128 v[208:211], v9 offset:25536
	s_waitcnt lgkmcnt(7)
	v_mfma_f32_16x16x32_bf16 v[36:39], v[212:215], v[92:95], v[36:39]
	ds_read_b128 v[212:215], v9 offset:33984
	s_waitcnt lgkmcnt(7)
	v_mfma_f32_16x16x32_bf16 v[40:43], v[234:237], v[92:95], v[40:43]
	ds_read_b128 v[234:237], v9 offset:256
	s_waitcnt lgkmcnt(7)
	v_mfma_f32_16x16x32_bf16 v[44:47], v[238:241], v[92:95], v[44:47]
	ds_read_b128 v[238:241], v9 offset:8704
	s_waitcnt lgkmcnt(7)
	v_mfma_f32_16x16x32_bf16 v[48:51], v[242:245], v[92:95], v[48:51]
	ds_read_b128 v[242:245], v9 offset:17152
	s_waitcnt lgkmcnt(7)
	v_mfma_f32_16x16x32_bf16 v[32:35], v[246:249], v[96:99], v[32:35]
	ds_read_b128 v[246:249], v9 offset:25600
	s_waitcnt lgkmcnt(7)
	v_mfma_f32_16x16x32_bf16 v[36:39], v[200:203], v[96:99], v[36:39]
	ds_read_b128 v[200:203], v9 offset:34048
	s_waitcnt lgkmcnt(7)
	v_mfma_f32_16x16x32_bf16 v[40:43], v[204:207], v[96:99], v[40:43]
	ds_read_b128 v[204:207], v9 offset:320
	s_waitcnt lgkmcnt(7)
	v_mfma_f32_16x16x32_bf16 v[44:47], v[208:211], v[96:99], v[44:47]
	ds_read_b128 v[208:211], v9 offset:8768
	s_waitcnt lgkmcnt(7)
	v_mfma_f32_16x16x32_bf16 v[48:51], v[212:215], v[96:99], v[48:51]
	ds_read_b128 v[212:215], v9 offset:17216
	s_waitcnt lgkmcnt(7)
	v_mfma_f32_16x16x32_bf16 v[32:35], v[234:237], v[100:103], v[32:35]
	ds_read_b128 v[234:237], v9 offset:25664
	s_waitcnt lgkmcnt(7)
	v_mfma_f32_16x16x32_bf16 v[36:39], v[238:241], v[100:103], v[36:39]
	ds_read_b128 v[238:241], v9 offset:34112
	s_waitcnt lgkmcnt(7)
	v_mfma_f32_16x16x32_bf16 v[40:43], v[242:245], v[100:103], v[40:43]
	ds_read_b128 v[242:245], v9 offset:384
	s_waitcnt lgkmcnt(7)
	v_mfma_f32_16x16x32_bf16 v[44:47], v[246:249], v[100:103], v[44:47]
	ds_read_b128 v[246:249], v9 offset:8832
	s_waitcnt lgkmcnt(7)
	v_mfma_f32_16x16x32_bf16 v[48:51], v[200:203], v[100:103], v[48:51]
	ds_read_b128 v[200:203], v9 offset:17280
	s_waitcnt lgkmcnt(7)
	v_mfma_f32_16x16x32_bf16 v[32:35], v[204:207], v[104:107], v[32:35]
	ds_read_b128 v[204:207], v9 offset:25728
	s_waitcnt lgkmcnt(7)
	v_mfma_f32_16x16x32_bf16 v[36:39], v[208:211], v[104:107], v[36:39]
	ds_read_b128 v[208:211], v9 offset:34176
	s_waitcnt lgkmcnt(7)
	v_mfma_f32_16x16x32_bf16 v[40:43], v[212:215], v[104:107], v[40:43]
	ds_read_b128 v[212:215], v9 offset:448
	s_waitcnt lgkmcnt(7)
	v_mfma_f32_16x16x32_bf16 v[44:47], v[234:237], v[104:107], v[44:47]
	ds_read_b128 v[234:237], v9 offset:8896
	s_waitcnt lgkmcnt(7)
	v_mfma_f32_16x16x32_bf16 v[48:51], v[238:241], v[104:107], v[48:51]
	ds_read_b128 v[238:241], v9 offset:17344
	s_waitcnt lgkmcnt(7)
	v_mfma_f32_16x16x32_bf16 v[32:35], v[242:245], v[108:111], v[32:35]
	ds_read_b128 v[242:245], v9 offset:25792
	s_waitcnt lgkmcnt(7)
	v_mfma_f32_16x16x32_bf16 v[36:39], v[246:249], v[108:111], v[36:39]
	ds_read_b128 v[246:249], v9 offset:34240
	s_waitcnt lgkmcnt(7)
	v_mfma_f32_16x16x32_bf16 v[40:43], v[200:203], v[108:111], v[40:43]
	s_waitcnt lgkmcnt(6)
	v_mfma_f32_16x16x32_bf16 v[44:47], v[204:207], v[108:111], v[44:47]
	s_waitcnt lgkmcnt(5)
	v_mfma_f32_16x16x32_bf16 v[48:51], v[208:211], v[108:111], v[48:51]
	s_waitcnt lgkmcnt(4)
	v_mfma_f32_16x16x32_bf16 v[32:35], v[212:215], v[112:115], v[32:35]
	s_waitcnt lgkmcnt(3)
	v_mfma_f32_16x16x32_bf16 v[36:39], v[234:237], v[112:115], v[36:39]
	s_waitcnt lgkmcnt(2)
	v_mfma_f32_16x16x32_bf16 v[40:43], v[238:241], v[112:115], v[40:43]
	s_waitcnt lgkmcnt(1)
	v_mfma_f32_16x16x32_bf16 v[44:47], v[242:245], v[112:115], v[44:47]
	s_waitcnt lgkmcnt(0)
	v_mfma_f32_16x16x32_bf16 v[48:51], v[246:249], v[112:115], v[48:51]
	global_load_dwordx4 v[52:55], v3, s[38:39]
	global_load_dwordx4 v[56:59], v3, s[38:39] offset:64
	global_load_dwordx4 v[60:63], v3, s[38:39] offset:128
	global_load_dwordx4 v[64:67], v3, s[38:39] offset:192
	global_load_dwordx4 v[68:71], v3, s[38:39] offset:256
	s_nop 7
	s_waitcnt vmcnt(0)
	v_add_f32_e32 v32, v32, v52
	v_add_f32_e32 v33, v33, v53
	v_add_f32_e32 v34, v34, v54
	v_add_f32_e32 v35, v35, v55
	v_add_f32_e32 v36, v36, v56
	v_add_f32_e32 v37, v37, v57
	v_add_f32_e32 v38, v38, v58
	v_add_f32_e32 v39, v39, v59
	v_add_f32_e32 v40, v40, v60
	v_add_f32_e32 v41, v41, v61
	v_add_f32_e32 v42, v42, v62
	v_add_f32_e32 v43, v43, v63
	v_add_f32_e32 v44, v44, v64
	v_add_f32_e32 v45, v45, v65
	v_add_f32_e32 v46, v46, v66
	v_add_f32_e32 v47, v47, v67
	v_add_f32_e32 v48, v48, v68
	v_add_f32_e32 v49, v49, v69
	v_add_f32_e32 v50, v50, v70
	v_add_f32_e32 v51, v51, v71
	s_nop 1
	global_store_dwordx4 v2, v[32:35], s[40:41]
	global_store_dwordx4 v2, v[36:39], s[40:41] offset:64
	global_store_dwordx4 v2, v[40:43], s[40:41] offset:128
	global_store_dwordx4 v2, v[44:47], s[40:41] offset:192
	global_store_dwordx4 v2, v[48:51], s[40:41] offset:256
	s_nop 1
	s_add_i32 s48, s48, s49
	s_cmpk_gt_u32 s48, 0x87
	s_cbranch_scc0 .Lmisc_pass
